# attention: removed the self-max NaN-quieting ops after the cross-lane exchanges (4 per key tile and map)
# baseline (speedup 1.0000x reference)
; #define LAS __attribute__((address_space(3)))
; __device__ __forceinline__ float shx(float v, int mask, int lane) { return __int_as_float(__builtin_amdgcn_ds_bpermute((lane ^ mask) << 2, __float_as_int(v))); }
; __device__ __forceinline__ void attn_phase(int wv, PP P, int L, LAS unsigned char* lds) {
;     ...
;                 bf16x8 pf[2][2];
; #pragma unroll
;                 for (int m = 0; m < 2; ++m) {
;                     f32x4 sa[4];
; #pragma unroll
;                     for (int nt = 0; nt < 4; ++nt) { sa[nt] = (f32x4){0.f, 0.f, 0.f, 0.f};
; #pragma unroll
;                         for (int kk = 0; kk < 2; ++kk) { const bf16x8 kf = *(const LAS bf16x8*)(lds + kbuf + (nt * 16 + fr) * 272 + (m * 64 + kk * 32 + fq * 8) * 2);
;                             sa[nt] = __builtin_amdgcn_mfma_f32_16x16x32_bf16(kf, qf[m][kk], sa[nt], 0, 0, 0); } }
;                     float mx = -INFINITY;
; #pragma unroll
;                     for (int nt = 0; nt < 4; ++nt)
; #pragma unroll
;                         for (int q = 0; q < 4; ++q) { const bool kv = (kt > 0) || (nt * 16 + fq * 4 + q >= 48); sa[nt][q] = kv ? sa[nt][q] * 0.125f : -INFINITY; mx = fmaxf(mx, sa[nt][q]); }
;                     mx = fmaxf(mx, shx(mx, 16, lane)); mx = fmaxf(mx, shx(mx, 32, lane));
;                     const float mnew = fmaxf(mrun[m], mx); const float alpha = __expf(mrun[m] - mnew); mrun[m] = mnew;
;                     float rsum = 0.f;
; #pragma unroll
;                     for (int nt = 0; nt < 4; ++nt)
; #pragma unroll
;                         for (int q = 0; q < 4; ++q) { sa[nt][q] = __expf(sa[nt][q] - mnew); rsum += sa[nt][q]; }
;                     rsum += shx(rsum, 16, lane); rsum += shx(rsum, 32, lane);
;                     lrun[m] = lrun[m] * alpha + rsum;
.LBB0_365:
	s_and_b64 s[26:27], s[6:7], s[18:19]
	v_cndmask_b32_e64 v36, 0, 1, s[26:27]
	s_lshl_b32 s24, s24, 1
	v_readfirstlane_b32 s9, v36
	s_sub_i32 s9, s24, s9
	s_and_b64 s[26:27], s[4:5], exec
	s_cselect_b32 s25, s9, -1
	s_cmp_lt_i32 s25, 0
	s_cbranch_scc1 .LBB0_367
	ds_read_b128 v[36:39], v171 offset:13056
	ds_read_b128 v[40:43], v171 offset:13120
	s_waitcnt vmcnt(1) lgkmcnt(1)
	v_mfma_f32_16x16x32_bf16 v[36:39], v[36:39], v[12:15], 0
	ds_read_b128 v[44:47], v171 offset:13248
	s_waitcnt lgkmcnt(1)
	v_mfma_f32_16x16x32_bf16 v[36:39], v[40:43], v[4:7], v[36:39]
	s_nop 7
	v_max3_f32 v40, v36, s52, v37
	v_max3_f32 v40, v40, v38, v39
	v_mov_b32_e32 v41, v40
	s_nop 1
	v_permlane16_swap_b32_e32 v40, v41
	s_waitcnt lgkmcnt(0)
	v_max_f32_e32 v40, v40, v41
	v_mov_b32_e32 v41, v40
	s_nop 1
	v_permlane32_swap_b32_e32 v40, v41
	s_waitcnt lgkmcnt(0)
	v_max_f32_e32 v40, v40, v41
	v_mul_f32_e32 v96, s50, v40
	v_fma_f32 v36, v36, s50, -v96
	v_exp_f32_e32 v53, v36
	v_fma_f32 v36, v37, s50, -v96
	v_exp_f32_e32 v57, v36
	v_fma_f32 v36, v38, s50, -v96
	v_sub_f32_e32 v40, 0xff800000, v96
	v_exp_f32_e32 v55, v36
	v_fma_f32 v36, v39, s50, -v96
	v_exp_f32_e32 v49, v40
	v_exp_f32_e32 v59, v36
	v_cvt_pk_bf16_f32 v36, v49, v49
	v_cvt_pk_bf16_f32 v40, v53, v57
	s_nop 0
	v_mov_b32_e32 v38, v36
	v_mov_b32_e32 v39, v36
	v_mov_b32_e32 v37, v36
	v_mov_b64_e32 v[66:67], v[38:39]
	v_mov_b32_e32 v66, v40
	ds_read_b128 v[40:43], v171 offset:13184
	s_waitcnt lgkmcnt(0)
	v_mfma_f32_16x16x32_bf16 v[40:43], v[40:43], v[8:11], 0
	v_cvt_pk_bf16_f32 v67, v55, v59
	v_mov_b64_e32 v[64:65], v[36:37]
	s_waitcnt vmcnt(0)
	v_mfma_f32_16x16x32_bf16 v[40:43], v[44:47], v[16:19], v[40:43]
	s_nop 7
	v_max3_f32 v44, v40, s52, v41
	v_max3_f32 v44, v44, v42, v43
	v_mov_b32_e32 v45, v44
	s_nop 1
	v_permlane16_swap_b32_e32 v44, v45
	s_waitcnt lgkmcnt(0)
	v_max_f32_e32 v44, v44, v45
	v_mov_b32_e32 v45, v44
	s_nop 1
	v_permlane32_swap_b32_e32 v44, v45
	s_waitcnt lgkmcnt(0)
	v_max_f32_e32 v44, v44, v45
	v_mul_f32_e32 v117, s50, v44
	v_sub_f32_e32 v44, 0xff800000, v117
	v_exp_f32_e32 v48, v44
	v_fma_f32 v40, v40, s50, -v117
	v_exp_f32_e32 v52, v40
	v_pk_add_f32 v[44:45], v[48:49], 0 op_sel_hi:[1,0]
	v_fma_f32 v40, v41, s50, -v117
	v_pk_add_f32 v[44:45], v[48:49], v[44:45]
	v_pk_add_f32 v[44:45], v[48:49], v[44:45]
	v_exp_f32_e32 v56, v40
	v_pk_add_f32 v[44:45], v[48:49], v[44:45]
	v_fma_f32 v40, v42, s50, -v117
	v_pk_add_f32 v[44:45], v[48:49], v[44:45]
	v_pk_add_f32 v[44:45], v[48:49], v[44:45]
	v_exp_f32_e32 v54, v40
	v_pk_add_f32 v[44:45], v[48:49], v[44:45]
	v_fma_f32 v40, v43, s50, -v117
	v_pk_add_f32 v[44:45], v[48:49], v[44:45]
	v_pk_add_f32 v[44:45], v[48:49], v[44:45]
	v_exp_f32_e32 v58, v40
	v_pk_add_f32 v[40:41], v[48:49], v[44:45]
	s_nop 0
	v_pk_add_f32 v[40:41], v[48:49], v[40:41]
	s_nop 0
	v_pk_add_f32 v[40:41], v[48:49], v[40:41]
	s_nop 0
	v_pk_add_f32 v[40:41], v[52:53], v[40:41]
	v_cvt_pk_bf16_f32 v52, v52, v56
	s_nop 0
	v_pk_add_f32 v[40:41], v[56:57], v[40:41]
	s_nop 0
	v_pk_add_f32 v[40:41], v[54:55], v[40:41]
	s_nop 0
	v_pk_add_f32 v[40:41], v[58:59], v[40:41]
	v_mov_b32_e32 v43, v41
	v_mov_b32_e32 v42, v40
	s_nop 0
	v_permlane16_swap_b32_e32 v41, v43
	v_permlane16_swap_b32_e32 v40, v42
	s_waitcnt lgkmcnt(0)
	v_pk_add_f32 v[40:41], v[40:41], v[42:43]
	v_mov_b32_e32 v43, v41
	v_mov_b32_e32 v42, v40
	s_nop 0
	v_permlane32_swap_b32_e32 v41, v43
	v_permlane32_swap_b32_e32 v40, v42
	s_waitcnt lgkmcnt(0)
; __device__ __forceinline__ float shx(float v, int mask, int lane) { return __int_as_float(__builtin_amdgcn_ds_bpermute((lane ^ mask) << 2, __float_as_int(v))); }
; __device__ __forceinline__ u32x2 trr(unsigned addr) { u32x2 r; asm volatile("ds_read_b64_tr_b16 %0, %1" : "=&v"(r) : "v"(addr) : "memory"); return r; }
; __device__ __forceinline__ void trw4(u32x2& a, u32x2& b, u32x2& c, u32x2& d) { asm volatile("s_waitcnt lgkmcnt(0)" : "+v"(a), "+v"(b), "+v"(c), "+v"(d) : : "memory"); }
; __device__ __forceinline__ void attn_phase(int wv, PP P, int L, LAS unsigned char* lds) {
;     ...
;                     float rsum = 0.f;
; #pragma unroll
;                     for (int nt = 0; nt < 4; ++nt)
; #pragma unroll
;                         for (int q = 0; q < 4; ++q) { sa[nt][q] = __expf(sa[nt][q] - mnew); rsum += sa[nt][q]; }
;                     rsum += shx(rsum, 16, lane); rsum += shx(rsum, 32, lane);
;                     lrun[m] = lrun[m] * alpha + rsum;
; #pragma unroll
;                     for (int e = 0; e < 8; ++e) O[m][e] *= alpha;
; #pragma unroll
;                     for (int kp = 0; kp < 2; ++kp) { u32x4 t; t.x = pack2(sa[2 * kp][0], sa[2 * kp][1]); t.y = pack2(sa[2 * kp][2], sa[2 * kp][3]); t.z = pack2(sa[2 * kp + 1][0], sa[2 * kp + 1][1]); t.w = pack2(sa[2 * kp + 1][2], sa[2 * kp + 1][3]);
;                         pf[m][kp] = __builtin_bit_cast(bf16x8, t); }
;                 }
;                 const unsigned trv = ldsb + vbuf + (4 * fq + trq) * 272 + (4 * trp) * 2;
; #pragma unroll
;                 for (int kp = 0; kp < 2; ++kp) {
;                     u32x2 vl[8], vh[8];
; #pragma unroll
;                     for (int e = 0; e < 8; ++e) { vl[e] = trr(trv + (32 * kp) * 272 + e * 32); vh[e] = trr(trv + (32 * kp + 16) * 272 + e * 32); }
;                     trw4(vl[0], vl[1], vl[2], vl[3]); trw4(vl[4], vl[5], vl[6], vl[7]); trw4(vh[0], vh[1], vh[2], vh[3]); trw4(vh[4], vh[5], vh[6], vh[7]);
; #pragma unroll
;                     for (int e = 0; e < 8; ++e) { const bf16x8 vf = mk8(vl[e], vh[e]);
;                         O[0][e] = __builtin_amdgcn_mfma_f32_16x16x32_bf16(vf, pf[0][kp], O[0][e], 0, 0, 0);
;                         O[1][e] = __builtin_amdgcn_mfma_f32_16x16x32_bf16(vf, pf[1][kp], O[1][e], 0, 0, 0); }
;                 }
	v_pk_add_f32 v[42:43], v[40:41], v[42:43]
	v_pk_mul_f32 v[40:41], v[48:49], 0 op_sel_hi:[1,0]
	v_pk_fma_f32 v[134:135], v[48:49], 0, v[42:43] op_sel_hi:[1,0,1]
	v_cvt_pk_bf16_f32 v48, v48, v48
	v_mov_b32_e32 v44, v41
	v_mov_b32_e32 v50, v48
	v_mov_b32_e32 v51, v48
	v_mov_b32_e32 v49, v48
	v_mov_b64_e32 v[94:95], v[50:51]
	v_mov_b32_e32 v94, v52
	ds_read_b64_tr_b16 v[52:53], v172
	v_cvt_pk_bf16_f32 v95, v54, v58
	ds_read_b64_tr_b16 v[54:55], v173
	ds_read_b64_tr_b16 v[56:57], v174
	ds_read_b64_tr_b16 v[58:59], v175
	ds_read_b64_tr_b16 v[60:61], v176
	ds_read_b64_tr_b16 v[62:63], v177
	ds_read_b64_tr_b16 v[68:69], v178
	ds_read_b64_tr_b16 v[70:71], v179
	ds_read_b64_tr_b16 v[72:73], v180
	ds_read_b64_tr_b16 v[74:75], v181
	ds_read_b64_tr_b16 v[76:77], v182
	ds_read_b64_tr_b16 v[78:79], v183
	ds_read_b64_tr_b16 v[80:81], v184
	ds_read_b64_tr_b16 v[82:83], v185
	ds_read_b64_tr_b16 v[84:85], v186
	ds_read_b64_tr_b16 v[86:87], v187
	s_nop 0
	s_waitcnt lgkmcnt(0)
	v_mov_b32_e32 v45, v41
	s_waitcnt lgkmcnt(0)
	s_waitcnt lgkmcnt(0)
	v_mov_b32_e32 v46, v41
	v_mov_b32_e32 v47, v41
	s_waitcnt lgkmcnt(0)
	v_mov_b32_e32 v41, v40
	v_mov_b32_e32 v42, v40
	v_mfma_f32_16x16x32_bf16 v[88:91], v[52:55], v[36:39], v[44:47]
	v_mov_b32_e32 v43, v40
	v_mov_b64_e32 v[92:93], v[48:49]
	v_mfma_f32_16x16x32_bf16 v[98:101], v[56:59], v[36:39], v[44:47]
	v_mfma_f32_16x16x32_bf16 v[102:105], v[60:63], v[36:39], v[44:47]
	v_mfma_f32_16x16x32_bf16 v[106:109], v[68:71], v[36:39], v[44:47]
	v_mfma_f32_16x16x32_bf16 v[110:113], v[72:75], v[36:39], v[44:47]
	v_mfma_f32_16x16x32_bf16 v[136:139], v[76:79], v[36:39], v[44:47]
	v_mfma_f32_16x16x32_bf16 v[144:147], v[80:83], v[36:39], v[44:47]
	v_mfma_f32_16x16x32_bf16 v[152:155], v[84:87], v[36:39], v[44:47]
	ds_read_b64_tr_b16 v[36:37], v188
	ds_read_b64_tr_b16 v[38:39], v189
	v_mfma_f32_16x16x32_bf16 v[52:55], v[52:55], v[48:51], v[40:43]
	v_mfma_f32_16x16x32_bf16 v[56:59], v[56:59], v[48:51], v[40:43]
	v_mfma_f32_16x16x32_bf16 v[60:63], v[60:63], v[48:51], v[40:43]
	v_mfma_f32_16x16x32_bf16 v[68:71], v[68:71], v[48:51], v[40:43]
	v_mfma_f32_16x16x32_bf16 v[118:121], v[72:75], v[48:51], v[40:43]
	v_mfma_f32_16x16x32_bf16 v[140:143], v[76:79], v[48:51], v[40:43]
	v_mfma_f32_16x16x32_bf16 v[148:151], v[80:83], v[48:51], v[40:43]
	v_mfma_f32_16x16x32_bf16 v[156:159], v[84:87], v[48:51], v[40:43]
	ds_read_b64_tr_b16 v[40:41], v190
	ds_read_b64_tr_b16 v[42:43], v191
	ds_read_b64_tr_b16 v[44:45], v192
	ds_read_b64_tr_b16 v[46:47], v193
	ds_read_b64_tr_b16 v[160:161], v194
	ds_read_b64_tr_b16 v[162:163], v195
	ds_read_b64_tr_b16 v[210:211], v197
	ds_read_b64_tr_b16 v[212:213], v202
	ds_read_b64_tr_b16 v[214:215], v203
	ds_read_b64_tr_b16 v[216:217], v204
	ds_read_b64_tr_b16 v[230:231], v205
	ds_read_b64_tr_b16 v[232:233], v206
	ds_read_b64_tr_b16 v[234:235], v207
	ds_read_b64_tr_b16 v[236:237], v208
	s_nop 0
	s_waitcnt lgkmcnt(0)
	s_waitcnt lgkmcnt(0)
	s_waitcnt lgkmcnt(0)
	s_waitcnt lgkmcnt(0)
	s_nop 0
	v_mfma_f32_16x16x32_bf16 v[72:75], v[36:39], v[64:67], v[88:91]
	v_mfma_f32_16x16x32_bf16 v[48:51], v[36:39], v[92:95], v[52:55]
	v_mfma_f32_16x16x32_bf16 v[84:87], v[40:43], v[64:67], v[98:101]
	v_mfma_f32_16x16x32_bf16 v[40:43], v[40:43], v[92:95], v[56:59]
	v_mfma_f32_16x16x32_bf16 v[80:83], v[44:47], v[64:67], v[102:105]
	v_mfma_f32_16x16x32_bf16 v[36:39], v[44:47], v[92:95], v[60:63]
	v_mfma_f32_16x16x32_bf16 v[76:79], v[160:163], v[64:67], v[106:109]
	v_mfma_f32_16x16x32_bf16 v[44:47], v[160:163], v[92:95], v[68:71]
	v_mfma_f32_16x16x32_bf16 v[88:91], v[210:213], v[64:67], v[110:113]
	v_mfma_f32_16x16x32_bf16 v[52:55], v[210:213], v[92:95], v[118:121]
	v_mfma_f32_16x16x32_bf16 v[108:111], v[214:217], v[64:67], v[136:139]
	v_mfma_f32_16x16x32_bf16 v[56:59], v[214:217], v[92:95], v[140:143]
	v_mfma_f32_16x16x32_bf16 v[112:115], v[230:233], v[64:67], v[144:147]
	v_mfma_f32_16x16x32_bf16 v[60:63], v[230:233], v[92:95], v[148:151]
	v_mfma_f32_16x16x32_bf16 v[68:71], v[234:237], v[64:67], v[152:155]
	v_mfma_f32_16x16x32_bf16 v[64:67], v[234:237], v[92:95], v[156:159]
	s_andn2_b64 vcc, exec, s[6:7]
	s_cbranch_vccz .LBB0_368
	s_branch .LBB0_375

; #define LAS __attribute__((address_space(3)))
; __device__ __forceinline__ float shx(float v, int mask, int lane) { return __int_as_float(__builtin_amdgcn_ds_bpermute((lane ^ mask) << 2, __float_as_int(v))); }
; __device__ __forceinline__ void attn_phase(int wv, PP P, int L, LAS unsigned char* lds) {
;     ...
;                 for (int m = 0; m < 2; ++m) {
;                     f32x4 sa[4];
; #pragma unroll
;                     for (int nt = 0; nt < 4; ++nt) { sa[nt] = (f32x4){0.f, 0.f, 0.f, 0.f};
; #pragma unroll
;                         for (int kk = 0; kk < 2; ++kk) { const bf16x8 kf = *(const LAS bf16x8*)(lds + kbuf + (nt * 16 + fr) * 272 + (m * 64 + kk * 32 + fq * 8) * 2);
;                             sa[nt] = __builtin_amdgcn_mfma_f32_16x16x32_bf16(kf, qf[m][kk], sa[nt], 0, 0, 0); } }
;                     float mx = -INFINITY;
; #pragma unroll
;                     for (int nt = 0; nt < 4; ++nt)
; #pragma unroll
;                         for (int q = 0; q < 4; ++q) { const bool kv = (kt > 0) || (nt * 16 + fq * 4 + q >= 48); sa[nt][q] = kv ? sa[nt][q] * 0.125f : -INFINITY; mx = fmaxf(mx, sa[nt][q]); }
;                     mx = fmaxf(mx, shx(mx, 16, lane)); mx = fmaxf(mx, shx(mx, 32, lane));
;                     const float mnew = fmaxf(mrun[m], mx); const float alpha = __expf(mrun[m] - mnew); mrun[m] = mnew;
;                     float rsum = 0.f;
; #pragma unroll
;                     for (int nt = 0; nt < 4; ++nt)
; #pragma unroll
;                         for (int q = 0; q < 4; ++q) { sa[nt][q] = __expf(sa[nt][q] - mnew); rsum += sa[nt][q]; }
;                     rsum += shx(rsum, 16, lane); rsum += shx(rsum, 32, lane);
;                     lrun[m] = lrun[m] * alpha + rsum;
; #pragma unroll
;                     for (int e = 0; e < 8; ++e) O[m][e] *= alpha;
.LBB0_373:
	v_add_u32_e32 v122, s7, v171
	ds_read_b128 v[92:95], v122
	ds_read_b128 v[98:101], v122 offset:64
	s_waitcnt lgkmcnt(1)
	v_mfma_f32_16x16x32_bf16 v[92:95], v[92:95], v[12:15], 0
	ds_read_b128 v[102:105], v122 offset:4416
	ds_read_b128 v[118:121], v122 offset:8768
	ds_read_b128 v[136:139], v122 offset:13120
	s_waitcnt lgkmcnt(3)
	v_mfma_f32_16x16x32_bf16 v[92:95], v[98:101], v[4:7], v[92:95]
	ds_read_b128 v[98:101], v122 offset:4352
	ds_read_b128 v[210:213], v122 offset:4544
	ds_read_b128 v[214:217], v122 offset:8896
	s_waitcnt lgkmcnt(2)
	v_mfma_f32_16x16x32_bf16 v[98:101], v[98:101], v[12:15], 0
	s_nop 2
	v_max3_f32 v97, v92, s52, v93
	v_mfma_f32_16x16x32_bf16 v[98:101], v[102:105], v[4:7], v[98:101]
	ds_read_b128 v[102:105], v122 offset:8704
	s_waitcnt lgkmcnt(0)
	v_mfma_f32_16x16x32_bf16 v[102:105], v[102:105], v[12:15], 0
	v_max3_f32 v97, v97, v94, v95
	s_nop 1
	v_mfma_f32_16x16x32_bf16 v[102:105], v[118:121], v[4:7], v[102:105]
	ds_read_b128 v[118:121], v122 offset:13056
	v_max3_f32 v97, v97, v98, v99
	s_waitcnt lgkmcnt(0)
	v_mfma_f32_16x16x32_bf16 v[118:121], v[118:121], v[12:15], 0
	v_max3_f32 v97, v97, v100, v101
	s_nop 0
	v_mfma_f32_16x16x32_bf16 v[160:163], v[136:139], v[4:7], v[118:121]
	s_nop 0
	v_max3_f32 v97, v97, v102, v103
	v_max3_f32 v97, v97, v104, v105
	s_nop 2
	s_nop 1
	v_max3_f32 v97, v97, v160, v161
	v_max3_f32 v97, v97, v162, v163
	v_mov_b32_e32 v106, v97
	s_nop 1
	v_permlane16_swap_b32_e32 v97, v106
	ds_read_b128 v[230:233], v122 offset:13248
	s_waitcnt lgkmcnt(1)
	v_max_f32_e32 v97, v97, v106
	v_mov_b32_e32 v106, v97
	s_nop 1
	v_permlane32_swap_b32_e32 v97, v106
	s_waitcnt lgkmcnt(0)
	v_max_f32_e32 v97, v97, v106
	v_mul_f32_e32 v97, s50, v97
	v_max_f32_e32 v131, v96, v97
	v_fma_f32 v92, v92, s50, -v131
	v_exp_f32_e32 v121, v92
	v_fma_f32 v92, v93, s50, -v131
	v_exp_f32_e32 v123, v92
	v_fma_f32 v92, v94, s50, -v131
	v_exp_f32_e32 v137, v92
	v_fma_f32 v92, v95, s50, -v131
	v_exp_f32_e32 v139, v92
	v_fma_f32 v92, v98, s50, -v131
	v_exp_f32_e32 v141, v92
	v_fma_f32 v92, v99, s50, -v131
	v_sub_f32_e32 v96, v96, v131
	v_exp_f32_e32 v143, v92
	v_fma_f32 v92, v100, s50, -v131
	v_exp_f32_e32 v145, v92
	v_fma_f32 v92, v101, s50, -v131
	v_exp_f32_e32 v116, v96
	v_exp_f32_e32 v147, v92
	v_fma_f32 v92, v102, s50, -v131
	v_exp_f32_e32 v149, v92
	v_fma_f32 v92, v103, s50, -v131
	v_pk_mul_f32 v[102:103], v[86:87], v[116:117] op_sel_hi:[1,0]
	v_pk_mul_f32 v[100:101], v[84:85], v[116:117] op_sel_hi:[1,0]
	v_pk_mul_f32 v[86:87], v[110:111], v[116:117] op_sel_hi:[1,0]
	v_pk_mul_f32 v[84:85], v[108:109], v[116:117] op_sel_hi:[1,0]
	ds_read_b128 v[108:111], v122 offset:128
	v_pk_mul_f32 v[98:99], v[82:83], v[116:117] op_sel_hi:[1,0]
	v_pk_mul_f32 v[96:97], v[80:81], v[116:117] op_sel_hi:[1,0]
	v_pk_mul_f32 v[82:83], v[114:115], v[116:117] op_sel_hi:[1,0]
	v_pk_mul_f32 v[80:81], v[112:113], v[116:117] op_sel_hi:[1,0]
	ds_read_b128 v[112:115], v122 offset:192
	s_waitcnt lgkmcnt(1)
	v_mfma_f32_16x16x32_bf16 v[108:111], v[108:111], v[8:11], 0
	v_exp_f32_e32 v151, v92
	v_fma_f32 v92, v104, s50, -v131
	s_waitcnt lgkmcnt(0)
	v_mfma_f32_16x16x32_bf16 v[108:111], v[112:115], v[16:19], v[108:111]
	ds_read_b128 v[112:115], v122 offset:4480
	v_exp_f32_e32 v153, v92
	s_waitcnt lgkmcnt(0)
	v_mfma_f32_16x16x32_bf16 v[112:115], v[112:115], v[8:11], 0
	s_nop 2
	s_nop 0
	v_max3_f32 v118, v108, s52, v109
	v_mfma_f32_16x16x32_bf16 v[112:115], v[210:213], v[16:19], v[112:115]
	ds_read_b128 v[210:213], v122 offset:8832
	s_waitcnt lgkmcnt(0)
	v_mfma_f32_16x16x32_bf16 v[210:213], v[210:213], v[8:11], 0
	v_max3_f32 v118, v118, v110, v111
	s_nop 1
	v_mfma_f32_16x16x32_bf16 v[210:213], v[214:217], v[16:19], v[210:213]
	ds_read_b128 v[214:217], v122 offset:13184
	v_max3_f32 v118, v118, v112, v113
	s_waitcnt lgkmcnt(0)
	v_mfma_f32_16x16x32_bf16 v[214:217], v[214:217], v[8:11], 0
	v_max3_f32 v118, v118, v114, v115
	s_nop 0
	v_mfma_f32_16x16x32_bf16 v[214:217], v[230:233], v[16:19], v[214:217]
	s_nop 0
	v_max3_f32 v118, v118, v210, v211
	v_max3_f32 v118, v118, v212, v213
	s_nop 2
	s_nop 1
	v_max3_f32 v118, v118, v214, v215
	v_max3_f32 v118, v118, v216, v217
	v_mov_b32_e32 v119, v118
	s_nop 1
	v_permlane16_swap_b32_e32 v118, v119
	v_fma_f32 v92, v105, s50, -v131
	v_exp_f32_e32 v155, v92
	v_fma_f32 v92, v160, s50, -v131
	s_waitcnt lgkmcnt(0)
	v_max_f32_e32 v118, v118, v119
	v_mov_b32_e32 v119, v118
	s_nop 1
	v_permlane32_swap_b32_e32 v118, v119
	v_exp_f32_e32 v157, v92
	v_fma_f32 v92, v161, s50, -v131
	s_waitcnt lgkmcnt(0)
; __device__ __forceinline__ float shx(float v, int mask, int lane) { return __int_as_float(__builtin_amdgcn_ds_bpermute((lane ^ mask) << 2, __float_as_int(v))); }
; __device__ __forceinline__ u32x2 trr(unsigned addr) { u32x2 r; asm volatile("ds_read_b64_tr_b16 %0, %1" : "=&v"(r) : "v"(addr) : "memory"); return r; }
; __device__ __forceinline__ unsigned pack2(float lo, float hi) { unsigned r; asm("v_cvt_pk_bf16_f32 %0, %1, %2" : "=v"(r) : "v"(lo), "v"(hi)); return r; }
; __device__ __forceinline__ void attn_phase(int wv, PP P, int L, LAS unsigned char* lds) {
;     ...
;                     const float mnew = fmaxf(mrun[m], mx); const float alpha = __expf(mrun[m] - mnew); mrun[m] = mnew;
;                     float rsum = 0.f;
; #pragma unroll
;                     for (int nt = 0; nt < 4; ++nt)
; #pragma unroll
;                         for (int q = 0; q < 4; ++q) { sa[nt][q] = __expf(sa[nt][q] - mnew); rsum += sa[nt][q]; }
;                     rsum += shx(rsum, 16, lane); rsum += shx(rsum, 32, lane);
;                     lrun[m] = lrun[m] * alpha + rsum;
; #pragma unroll
;                     for (int e = 0; e < 8; ++e) O[m][e] *= alpha;
; #pragma unroll
;                     for (int kp = 0; kp < 2; ++kp) { u32x4 t; t.x = pack2(sa[2 * kp][0], sa[2 * kp][1]); t.y = pack2(sa[2 * kp][2], sa[2 * kp][3]); t.z = pack2(sa[2 * kp + 1][0], sa[2 * kp + 1][1]); t.w = pack2(sa[2 * kp + 1][2], sa[2 * kp + 1][3]);
;                         pf[m][kp] = __builtin_bit_cast(bf16x8, t); }
;                 }
;                 const unsigned trv = ldsb + vbuf + (4 * fq + trq) * 272 + (4 * trp) * 2;
; #pragma unroll
;                 for (int kp = 0; kp < 2; ++kp) {
;                     u32x2 vl[8], vh[8];
; #pragma unroll
;                     for (int e = 0; e < 8; ++e) { vl[e] = trr(trv + (32 * kp) * 272 + e * 32); vh[e] = trr(trv + (32 * kp + 16) * 272 + e * 32); }
	v_max_f32_e32 v118, v118, v119
	v_mul_f32_e32 v118, s50, v118
	v_max_f32_e32 v209, v117, v118
	v_fma_f32 v108, v108, s50, -v209
	v_exp_f32_e32 v120, v108
	v_fma_f32 v108, v109, s50, -v209
	v_exp_f32_e32 v122, v108
	v_fma_f32 v108, v110, s50, -v209
	v_exp_f32_e32 v136, v108
	v_fma_f32 v108, v111, s50, -v209
	v_exp_f32_e32 v138, v108
	v_fma_f32 v108, v112, s50, -v209
	v_exp_f32_e32 v140, v108
	v_fma_f32 v108, v113, s50, -v209
	v_exp_f32_e32 v142, v108
	v_fma_f32 v108, v114, s50, -v209
	v_exp_f32_e32 v144, v108
	v_fma_f32 v108, v115, s50, -v209
	v_fma_f32 v110, v211, s50, -v209
	v_exp_f32_e32 v146, v108
	v_fma_f32 v108, v210, s50, -v209
	v_exp_f32_e32 v150, v110
	v_fma_f32 v110, v212, s50, -v209
	v_exp_f32_e32 v148, v108
	v_pk_add_f32 v[108:109], v[120:121], 0 op_sel_hi:[1,0]
	v_pk_add_f32 v[108:109], v[122:123], v[108:109]
	v_exp_f32_e32 v152, v110
	v_fma_f32 v110, v213, s50, -v209
	v_pk_add_f32 v[108:109], v[136:137], v[108:109]
	v_pk_add_f32 v[108:109], v[138:139], v[108:109]
	v_exp_f32_e32 v154, v110
	v_fma_f32 v110, v214, s50, -v209
	v_pk_add_f32 v[108:109], v[140:141], v[108:109]
	v_pk_add_f32 v[108:109], v[142:143], v[108:109]
	v_exp_f32_e32 v156, v110
	v_fma_f32 v110, v215, s50, -v209
	v_pk_add_f32 v[108:109], v[144:145], v[108:109]
	v_exp_f32_e32 v159, v92
	v_fma_f32 v92, v162, s50, -v131
	v_pk_add_f32 v[108:109], v[146:147], v[108:109]
	v_exp_f32_e32 v158, v110
	v_fma_f32 v110, v216, s50, -v209
	v_pk_add_f32 v[108:109], v[148:149], v[108:109]
	v_exp_f32_e32 v161, v92
	v_fma_f32 v92, v163, s50, -v131
	v_exp_f32_e32 v160, v110
	v_fma_f32 v110, v217, s50, -v209
	v_pk_add_f32 v[108:109], v[150:151], v[108:109]
	v_pk_add_f32 v[108:109], v[152:153], v[108:109]
	v_exp_f32_e32 v163, v92
	v_exp_f32_e32 v162, v110
	v_pk_add_f32 v[108:109], v[154:155], v[108:109]
	v_pk_mul_f32 v[106:107], v[74:75], v[116:117] op_sel_hi:[1,0]
	v_pk_add_f32 v[108:109], v[156:157], v[108:109]
	v_pk_mul_f32 v[104:105], v[72:73], v[116:117] op_sel_hi:[1,0]
	v_pk_add_f32 v[108:109], v[158:159], v[108:109]
	v_pk_mul_f32 v[94:95], v[78:79], v[116:117] op_sel_hi:[1,0]
	v_pk_add_f32 v[108:109], v[160:161], v[108:109]
	v_pk_mul_f32 v[92:93], v[76:77], v[116:117] op_sel_hi:[1,0]
	v_pk_add_f32 v[108:109], v[162:163], v[108:109]
	v_mov_b32_e32 v111, v109
	v_mov_b32_e32 v110, v108
	s_nop 0
	v_permlane16_swap_b32_e32 v109, v111
	v_permlane16_swap_b32_e32 v108, v110
	v_pk_mul_f32 v[90:91], v[90:91], v[116:117] op_sel_hi:[1,0]
	v_pk_mul_f32 v[88:89], v[88:89], v[116:117] op_sel_hi:[1,0]
	v_pk_mul_f32 v[74:75], v[70:71], v[116:117] op_sel_hi:[1,0]
	v_pk_mul_f32 v[72:73], v[68:69], v[116:117] op_sel_hi:[1,0]
	s_waitcnt lgkmcnt(0)
	v_pk_add_f32 v[108:109], v[108:109], v[110:111]
	v_sub_f32_e32 v117, v117, v209
	v_mov_b32_e32 v111, v109
	v_mov_b32_e32 v110, v108
	s_nop 0
	v_permlane32_swap_b32_e32 v109, v111
	v_permlane32_swap_b32_e32 v108, v110
	v_exp_f32_e32 v214, v117
	v_mov_b32_e32 v215, v116
	v_add_u32_e32 v216, s7, v167
	s_waitcnt lgkmcnt(0)
	v_pk_add_f32 v[108:109], v[108:109], v[110:111]
	v_pk_mul_f32 v[116:117], v[40:41], v[214:215] op_sel_hi:[1,0]
	v_pk_fma_f32 v[134:135], v[134:135], v[214:215], v[108:109]
	v_pk_mul_f32 v[108:109], v[44:45], v[214:215] op_sel_hi:[1,0]
	v_pk_mul_f32 v[44:45], v[56:57], v[214:215] op_sel_hi:[1,0]
	v_pk_mul_f32 v[40:41], v[60:61], v[214:215] op_sel_hi:[1,0]
	ds_read_b64_tr_b16 v[60:61], v216 offset:34816
	v_pk_mul_f32 v[118:119], v[42:43], v[214:215] op_sel_hi:[1,0]
	v_pk_mul_f32 v[42:43], v[62:63], v[214:215] op_sel_hi:[1,0]
	ds_read_b64_tr_b16 v[62:63], v216 offset:39168
	v_cvt_pk_bf16_f32 v77, v137, v139
	v_pk_mul_f32 v[210:211], v[48:49], v[214:215] op_sel_hi:[1,0]
	v_pk_mul_f32 v[48:49], v[52:53], v[214:215] op_sel_hi:[1,0]
	v_cvt_pk_bf16_f32 v53, v136, v138
	ds_read_b64_tr_b16 v[136:137], v216 offset:34848
	ds_read_b64_tr_b16 v[138:139], v216 offset:39200
	v_cvt_pk_bf16_f32 v78, v141, v143
	v_pk_mul_f32 v[212:213], v[50:51], v[214:215] op_sel_hi:[1,0]
	v_pk_mul_f32 v[50:51], v[54:55], v[214:215] op_sel_hi:[1,0]
	v_cvt_pk_bf16_f32 v54, v140, v142
	ds_read_b64_tr_b16 v[140:141], v216 offset:34880
	ds_read_b64_tr_b16 v[142:143], v216 offset:39232
	v_cvt_pk_bf16_f32 v79, v145, v147
	v_cvt_pk_bf16_f32 v55, v144, v146
	ds_read_b64_tr_b16 v[144:145], v216 offset:34912
	ds_read_b64_tr_b16 v[146:147], v216 offset:39264
	v_cvt_pk_bf16_f32 v68, v149, v151
	v_pk_mul_f32 v[112:113], v[36:37], v[214:215] op_sel_hi:[1,0]
	v_pk_mul_f32 v[36:37], v[64:65], v[214:215] op_sel_hi:[1,0]
	v_cvt_pk_bf16_f32 v64, v148, v150
	ds_read_b64_tr_b16 v[148:149], v216 offset:34944
	ds_read_b64_tr_b16 v[150:151], v216 offset:39296
	v_cvt_pk_bf16_f32 v69, v153, v155
	v_cvt_pk_bf16_f32 v65, v152, v154
	ds_read_b64_tr_b16 v[152:153], v216 offset:34976
	ds_read_b64_tr_b16 v[154:155], v216 offset:39328
	v_cvt_pk_bf16_f32 v70, v157, v159
	v_pk_mul_f32 v[114:115], v[38:39], v[214:215] op_sel_hi:[1,0]
	v_pk_mul_f32 v[38:39], v[66:67], v[214:215] op_sel_hi:[1,0]
	v_cvt_pk_bf16_f32 v66, v156, v158
	ds_read_b64_tr_b16 v[156:157], v216 offset:35008
	ds_read_b64_tr_b16 v[158:159], v216 offset:39360
	v_cvt_pk_bf16_f32 v76, v121, v123
	v_cvt_pk_bf16_f32 v52, v120, v122
	ds_read_b64_tr_b16 v[120:121], v216 offset:35040
	ds_read_b64_tr_b16 v[122:123], v216 offset:39392
	s_waitcnt lgkmcnt(0)
; __device__ __forceinline__ u32x2 trr(unsigned addr) { u32x2 r; asm volatile("ds_read_b64_tr_b16 %0, %1" : "=&v"(r) : "v"(addr) : "memory"); return r; }
; __device__ __forceinline__ void trw4(u32x2& a, u32x2& b, u32x2& c, u32x2& d) { asm volatile("s_waitcnt lgkmcnt(0)" : "+v"(a), "+v"(b), "+v"(c), "+v"(d) : : "memory"); }
; __device__ __forceinline__ void attn_phase(int wv, PP P, int L, LAS unsigned char* lds) {
;     ...
;                 const unsigned trv = ldsb + vbuf + (4 * fq + trq) * 272 + (4 * trp) * 2;
; #pragma unroll
;                 for (int kp = 0; kp < 2; ++kp) {
;                     u32x2 vl[8], vh[8];
; #pragma unroll
;                     for (int e = 0; e < 8; ++e) { vl[e] = trr(trv + (32 * kp) * 272 + e * 32); vh[e] = trr(trv + (32 * kp + 16) * 272 + e * 32); }
;                     trw4(vl[0], vl[1], vl[2], vl[3]); trw4(vl[4], vl[5], vl[6], vl[7]); trw4(vh[0], vh[1], vh[2], vh[3]); trw4(vh[4], vh[5], vh[6], vh[7]);
; #pragma unroll
;                     for (int e = 0; e < 8; ++e) { const bf16x8 vf = mk8(vl[e], vh[e]);
;                         O[0][e] = __builtin_amdgcn_mfma_f32_16x16x32_bf16(vf, pf[0][kp], O[0][e], 0, 0, 0);
;                         O[1][e] = __builtin_amdgcn_mfma_f32_16x16x32_bf16(vf, pf[1][kp], O[1][e], 0, 0, 0); }
;                 }
	s_waitcnt lgkmcnt(0)
	s_waitcnt lgkmcnt(0)
	v_pk_mul_f32 v[110:111], v[46:47], v[214:215] op_sel_hi:[1,0]
	v_pk_mul_f32 v[46:47], v[58:59], v[214:215] op_sel_hi:[1,0]
	s_waitcnt lgkmcnt(0)
	v_mfma_f32_16x16x32_bf16 v[56:59], v[60:63], v[76:79], v[104:107]
	v_cvt_pk_bf16_f32 v71, v161, v163
	v_cvt_pk_bf16_f32 v67, v160, v162
	v_mfma_f32_16x16x32_bf16 v[100:103], v[136:139], v[76:79], v[100:103]
	v_mfma_f32_16x16x32_bf16 v[104:107], v[136:139], v[52:55], v[116:119]
	v_mfma_f32_16x16x32_bf16 v[96:99], v[140:143], v[76:79], v[96:99]
	v_mfma_f32_16x16x32_bf16 v[112:115], v[140:143], v[52:55], v[112:115]
	v_mfma_f32_16x16x32_bf16 v[136:139], v[152:155], v[76:79], v[84:87]
	v_mfma_f32_16x16x32_bf16 v[140:143], v[152:155], v[52:55], v[44:47]
	v_mfma_f32_16x16x32_bf16 v[152:155], v[120:123], v[76:79], v[72:75]
	s_nop 1
	v_mfma_f32_16x16x32_bf16 v[120:123], v[120:123], v[52:55], v[36:39]
	s_nop 2
	ds_read_b64_tr_b16 v[36:37], v216 offset:43520
	v_mfma_f32_16x16x32_bf16 v[88:91], v[148:151], v[76:79], v[88:91]
	v_mfma_f32_16x16x32_bf16 v[116:119], v[148:151], v[52:55], v[48:51]
	v_mfma_f32_16x16x32_bf16 v[148:151], v[156:159], v[52:55], v[40:43]
	s_nop 1
	ds_read_b64_tr_b16 v[38:39], v216 offset:47872
	ds_read_b64_tr_b16 v[40:41], v216 offset:43552
	ds_read_b64_tr_b16 v[42:43], v216 offset:47904
	ds_read_b64_tr_b16 v[44:45], v216 offset:43584
	ds_read_b64_tr_b16 v[46:47], v216 offset:47936
	v_mfma_f32_16x16x32_bf16 v[60:63], v[60:63], v[52:55], v[210:213]
	v_mfma_f32_16x16x32_bf16 v[108:111], v[144:147], v[52:55], v[108:111]
	ds_read_b64_tr_b16 v[52:53], v216 offset:43616
	ds_read_b64_tr_b16 v[54:55], v216 offset:47968
	v_mfma_f32_16x16x32_bf16 v[92:95], v[144:147], v[76:79], v[92:95]
	v_mfma_f32_16x16x32_bf16 v[144:147], v[156:159], v[76:79], v[80:83]
	ds_read_b64_tr_b16 v[156:157], v216 offset:43648
	ds_read_b64_tr_b16 v[158:159], v216 offset:48000
	ds_read_b64_tr_b16 v[160:161], v216 offset:43680
	ds_read_b64_tr_b16 v[162:163], v216 offset:48032
	ds_read_b64_tr_b16 v[210:211], v216 offset:43712
	ds_read_b64_tr_b16 v[212:213], v216 offset:48064
	ds_read_b64_tr_b16 v[214:215], v216 offset:43744
	ds_read_b64_tr_b16 v[216:217], v216 offset:48096
	s_waitcnt lgkmcnt(0)
	s_waitcnt lgkmcnt(0)
	s_waitcnt lgkmcnt(0)
	s_nop 0
	s_waitcnt lgkmcnt(0)
	v_mfma_f32_16x16x32_bf16 v[72:75], v[36:39], v[68:71], v[56:59]
	v_mfma_f32_16x16x32_bf16 v[48:51], v[36:39], v[64:67], v[60:63]
	v_mfma_f32_16x16x32_bf16 v[84:87], v[40:43], v[68:71], v[100:103]
	v_mfma_f32_16x16x32_bf16 v[40:43], v[40:43], v[64:67], v[104:107]
	v_mfma_f32_16x16x32_bf16 v[80:83], v[44:47], v[68:71], v[96:99]
	v_mfma_f32_16x16x32_bf16 v[36:39], v[44:47], v[64:67], v[112:115]
	s_nop 1
	v_mov_b32_e32 v96, v131
	v_mfma_f32_16x16x32_bf16 v[76:79], v[52:55], v[68:71], v[92:95]
	v_mfma_f32_16x16x32_bf16 v[44:47], v[52:55], v[64:67], v[108:111]
	v_mfma_f32_16x16x32_bf16 v[88:91], v[156:159], v[68:71], v[88:91]
	v_mfma_f32_16x16x32_bf16 v[52:55], v[156:159], v[64:67], v[116:119]
	v_mfma_f32_16x16x32_bf16 v[108:111], v[160:163], v[68:71], v[136:139]
	s_nop 1
	v_mov_b32_e32 v117, v209
	v_mfma_f32_16x16x32_bf16 v[56:59], v[160:163], v[64:67], v[140:143]
	v_mfma_f32_16x16x32_bf16 v[112:115], v[210:213], v[68:71], v[144:147]
	v_mfma_f32_16x16x32_bf16 v[60:63], v[210:213], v[64:67], v[148:151]
	v_mfma_f32_16x16x32_bf16 v[68:71], v[214:217], v[68:71], v[152:155]
	v_mfma_f32_16x16x32_bf16 v[64:67], v[214:217], v[64:67], v[120:123]
	s_cmp_eq_u32 s24, s6
	s_cbranch_scc1 .LBB0_375
